# gating mixer quarter loop: even quarters load the v tile of both quarters of the pair (both 64-byte halves of each 128-byte line requested together, second half into idle registers), odd quarters copy
# speedup vs baseline: 1.0100x; 1.0100x over previous
; #define LAS __attribute__((address_space(3)))
; __device__ __forceinline__ unsigned pk2(float lo, float hi) { return f2bf(lo) | (f2bf(hi) << 16); }
; __device__ __forceinline__ float bflo(unsigned w) { return __uint_as_float(w << 16); }
; __device__ __forceinline__ float bfhi(unsigned w) { return __uint_as_float(w & 0xffff0000u); }
; __device__ __forceinline__ void sgu_item(LAS unsigned char* wl, const bf16* proj, bf16* ymix, const float* vstat, const float* sgu_g, const bf16* Wm, const float* sgu_b, int chunk, int h, int lane) {
;     ...
;     for (int dq = 0; dq < 4; ++dq) {
;         const int colv = h * 128 + dq * 32;
;         v4u raw[8];
; #pragma unroll
;         for (int i = 0; i < 8; ++i) raw[i] = __builtin_nontemporal_load((const v4u*)(proj + (R0 + rsub + 16 * i) * DIN + 1024 + colv + c16 * 8));
;         const f32x4 g0 = *(const f32x4*)(sgu_g + colv + c16 * 8), g1 = *(const f32x4*)(sgu_g + colv + c16 * 8 + 4);
; #pragma unroll
;         for (int i = 0; i < 8; ++i) { const int s = rsub + 16 * i; const f32x2 ms = st[s]; const v4u w = raw[i];
;             v2u lo, hi; lo.x = pk2((bflo(w.x) - ms.x) * ms.y * g0[0], (bfhi(w.x) - ms.x) * ms.y * g0[1]); lo.y = pk2((bflo(w.y) - ms.x) * ms.y * g0[2], (bfhi(w.y) - ms.x) * ms.y * g0[3]);
;             hi.x = pk2((bflo(w.z) - ms.x) * ms.y * g1[0], (bfhi(w.z) - ms.x) * ms.y * g1[1]); hi.y = pk2((bflo(w.w) - ms.x) * ms.y * g1[2], (bfhi(w.w) - ms.x) * ms.y * g1[3]);
;             *(LAS v2u*)(wl + s * VP2 + (4 * c16) * 2) = lo; *(LAS v2u*)(wl + s * VP2 + (16 + 4 * c16) * 2) = hi; }
.LBB0_511:
	s_bitcmp1_b32 s20, 6
	s_cbranch_scc0 .Lsgu_even
	s_mov_b32 s0, 0xf100000
	s_waitcnt lgkmcnt(0)
	global_load_dwordx4 v[88:91], v[178:179], off
	global_load_dwordx4 v[92:95], v[178:179], off offset:-16
	v_mov_b32_e32 v118, v140
	v_mov_b32_e32 v119, v141
	v_mov_b32_e32 v120, v142
	v_mov_b32_e32 v121, v143
	v_mov_b32_e32 v112, v144
	v_mov_b32_e32 v113, v145
	v_mov_b32_e32 v114, v146
	v_mov_b32_e32 v115, v147
	v_mov_b32_e32 v108, v148
	v_mov_b32_e32 v109, v149
	v_mov_b32_e32 v110, v150
	v_mov_b32_e32 v111, v151
	v_mov_b32_e32 v104, v152
	v_mov_b32_e32 v105, v153
	v_mov_b32_e32 v106, v154
	v_mov_b32_e32 v107, v155
	v_mov_b32_e32 v100, v156
	v_mov_b32_e32 v101, v157
	v_mov_b32_e32 v102, v158
	v_mov_b32_e32 v103, v159
	v_mov_b32_e32 v96, v238
	v_mov_b32_e32 v97, v239
	v_mov_b32_e32 v98, v240
	v_mov_b32_e32 v99, v241
	v_mov_b32_e32 v84, v248
	v_mov_b32_e32 v85, v249
	v_mov_b32_e32 v86, v250
	v_mov_b32_e32 v87, v251
	v_mov_b32_e32 v80, v160
	v_mov_b32_e32 v81, v161
	v_mov_b32_e32 v82, v242
	v_mov_b32_e32 v83, v243
	s_waitcnt vmcnt(0)
	s_branch .Lsgu_go
.Lsgu_even:
	v_lshl_add_u64 v[80:81], v[198:199], 0, s[20:21]
	v_add_co_u32_e32 v82, vcc, 0xf100000, v80
	s_mov_b32 s0, 0xf100000
	s_nop 0
	v_addc_co_u32_e32 v83, vcc, 0, v81, vcc
	global_load_dwordx4 v[118:121], v[82:83], off offset:2048 nt
	global_load_dwordx4 v[140:143], v[82:83], off offset:2112 nt
	v_add_co_u32_e32 v82, vcc, 0xf10c000, v80
	s_waitcnt lgkmcnt(0)
	s_nop 0
	v_addc_co_u32_e32 v83, vcc, 0, v81, vcc
	global_load_dwordx4 v[112:115], v[82:83], off offset:2048 nt
	global_load_dwordx4 v[144:147], v[82:83], off offset:2112 nt
	v_add_co_u32_e32 v82, vcc, 0xf118000, v80
	s_nop 0
	s_nop 0
	v_addc_co_u32_e32 v83, vcc, 0, v81, vcc
	global_load_dwordx4 v[108:111], v[82:83], off offset:2048 nt
	global_load_dwordx4 v[148:151], v[82:83], off offset:2112 nt
	v_add_co_u32_e32 v82, vcc, 0xf124000, v80
	s_nop 0
	s_nop 0
	v_addc_co_u32_e32 v83, vcc, 0, v81, vcc
	global_load_dwordx4 v[104:107], v[82:83], off offset:2048 nt
	global_load_dwordx4 v[152:155], v[82:83], off offset:2112 nt
	v_add_co_u32_e32 v82, vcc, 0xf130000, v80
	s_nop 0
	s_nop 0
	v_addc_co_u32_e32 v83, vcc, 0, v81, vcc
	global_load_dwordx4 v[100:103], v[82:83], off offset:2048 nt
	global_load_dwordx4 v[156:159], v[82:83], off offset:2112 nt
	v_add_co_u32_e32 v82, vcc, 0xf13c000, v80
	s_nop 1
	v_addc_co_u32_e32 v83, vcc, 0, v81, vcc
	global_load_dwordx4 v[96:99], v[82:83], off offset:2048 nt
	global_load_dwordx4 v[238:241], v[82:83], off offset:2112 nt
	v_add_co_u32_e32 v82, vcc, 0xf148000, v80
	s_nop 1
	v_addc_co_u32_e32 v83, vcc, 0, v81, vcc
	v_add_co_u32_e32 v80, vcc, 0xf154000, v80
	global_load_dwordx4 v[84:87], v[82:83], off offset:2048 nt
	global_load_dwordx4 v[248:251], v[82:83], off offset:2112 nt
	s_nop 0
	v_addc_co_u32_e32 v81, vcc, 0, v81, vcc
	global_load_dwordx2 v[160:161], v[80:81], off offset:2112 nt
	global_load_dwordx2 v[242:243], v[80:81], off offset:2120 nt
	global_load_dwordx4 v[80:83], v[80:81], off offset:2048 nt
	s_nop 0
	global_load_dwordx4 v[88:91], v[178:179], off
	global_load_dwordx4 v[92:95], v[178:179], off offset:-16
	s_waitcnt vmcnt(0)
.Lsgu_go:
	v_lshlrev_b32_e32 v117, 16, v119
	v_lshlrev_b32_e32 v116, 16, v118
	v_and_b32_e32 v119, 0xffff0000, v119
	v_and_b32_e32 v118, 0xffff0000, v118
	ds_read_b64 v[122:123], v218 offset:10240
	v_lshl_add_u64 v[178:179], v[178:179], 0, s[88:89]
	s_waitcnt lgkmcnt(0)
	v_pk_add_f32 v[116:117], v[116:117], v[122:123] op_sel_hi:[1,0] neg_lo:[0,1] neg_hi:[0,1]
	s_nop 0
	v_pk_mul_f32 v[124:125], v[122:123], v[116:117] op_sel:[1,0]
	v_pk_add_f32 v[118:119], v[118:119], v[122:123] op_sel_hi:[1,0] neg_lo:[0,1] neg_hi:[0,1]
	s_waitcnt vmcnt(0)
	v_mov_b32_e32 v116, v92
	v_mov_b32_e32 v117, v94
	v_pk_mul_f32 v[124:125], v[116:117], v[124:125]
	v_pk_mul_f32 v[118:119], v[122:123], v[118:119] op_sel:[1,0]
	v_mov_b32_e32 v94, v93
	v_pk_mul_f32 v[92:93], v[94:95], v[118:119]
	v_and_b32_sdwa v118, v125, v245 dst_sel:DWORD dst_unused:UNUSED_PAD src0_sel:WORD_1 src1_sel:DWORD
	v_and_b32_sdwa v119, v124, v245 dst_sel:DWORD dst_unused:UNUSED_PAD src0_sel:WORD_1 src1_sel:DWORD
	v_add3_u32 v124, v124, v119, s68
	v_add3_u32 v118, v125, v118, s68
	v_and_b32_sdwa v119, v93, v245 dst_sel:DWORD dst_unused:UNUSED_PAD src0_sel:WORD_1 src1_sel:DWORD
	v_and_b32_sdwa v125, v92, v245 dst_sel:DWORD dst_unused:UNUSED_PAD src0_sel:WORD_1 src1_sel:DWORD
	v_add3_u32 v93, v93, v119, s68
	v_add3_u32 v92, v92, v125, s68
	v_and_b32_e32 v93, 0xffff0000, v93
	v_and_b32_e32 v92, 0xffff0000, v92
	v_or_b32_sdwa v119, v93, v118 dst_sel:DWORD dst_unused:UNUSED_PAD src0_sel:DWORD src1_sel:WORD_1
	v_or_b32_sdwa v118, v92, v124 dst_sel:DWORD dst_unused:UNUSED_PAD src0_sel:DWORD src1_sel:WORD_1
	v_lshlrev_b32_e32 v93, 16, v121
	v_lshlrev_b32_e32 v92, 16, v120
	v_and_b32_e32 v121, 0xffff0000, v121
	v_and_b32_e32 v120, 0xffff0000, v120
	v_pk_add_f32 v[92:93], v[92:93], v[122:123] op_sel_hi:[1,0] neg_lo:[0,1] neg_hi:[0,1]
	v_pk_add_f32 v[120:121], v[120:121], v[122:123] op_sel_hi:[1,0] neg_lo:[0,1] neg_hi:[0,1]
	v_pk_mul_f32 v[124:125], v[122:123], v[92:93] op_sel:[1,0]
	v_mov_b32_e32 v93, v90
	v_pk_mul_f32 v[120:121], v[122:123], v[120:121] op_sel:[1,0]
	v_mov_b32_e32 v90, v89
	v_mov_b32_e32 v92, v88
	v_pk_mul_f32 v[88:89], v[90:91], v[120:121]
	v_pk_mul_f32 v[124:125], v[92:93], v[124:125]
	v_and_b32_sdwa v122, v89, v245 dst_sel:DWORD dst_unused:UNUSED_PAD src0_sel:WORD_1 src1_sel:DWORD
	v_and_b32_sdwa v123, v88, v245 dst_sel:DWORD dst_unused:UNUSED_PAD src0_sel:WORD_1 src1_sel:DWORD
	v_and_b32_sdwa v120, v125, v245 dst_sel:DWORD dst_unused:UNUSED_PAD src0_sel:WORD_1 src1_sel:DWORD
	v_and_b32_sdwa v121, v124, v245 dst_sel:DWORD dst_unused:UNUSED_PAD src0_sel:WORD_1 src1_sel:DWORD
	v_add3_u32 v89, v89, v122, s68
	v_add3_u32 v88, v88, v123, s68
	v_add3_u32 v121, v124, v121, s68
	v_add3_u32 v120, v125, v120, s68
	v_and_b32_e32 v89, 0xffff0000, v89
	v_and_b32_e32 v88, 0xffff0000, v88
	v_or_b32_sdwa v89, v89, v120 dst_sel:DWORD dst_unused:UNUSED_PAD src0_sel:DWORD src1_sel:WORD_1
	v_or_b32_sdwa v88, v88, v121 dst_sel:DWORD dst_unused:UNUSED_PAD src0_sel:DWORD src1_sel:WORD_1
	ds_write2_b64 v219, v[118:119], v[88:89] offset1:4
	ds_read_b64 v[88:89], v218 offset:10368
	v_lshlrev_b32_e32 v119, 16, v113
	v_lshlrev_b32_e32 v118, 16, v112
	v_and_b32_e32 v113, 0xffff0000, v113
	v_and_b32_e32 v112, 0xffff0000, v112
	s_waitcnt lgkmcnt(0)
; #define LAS __attribute__((address_space(3)))
; __device__ __forceinline__ unsigned pk2(float lo, float hi) { return f2bf(lo) | (f2bf(hi) << 16); }
; __device__ __forceinline__ float bflo(unsigned w) { return __uint_as_float(w << 16); }
; __device__ __forceinline__ float bfhi(unsigned w) { return __uint_as_float(w & 0xffff0000u); }
; __device__ __forceinline__ void sgu_item(LAS unsigned char* wl, const bf16* proj, bf16* ymix, const float* vstat, const float* sgu_g, const bf16* Wm, const float* sgu_b, int chunk, int h, int lane) {
;     ...
;         for (int i = 0; i < 8; ++i) { const int s = rsub + 16 * i; const f32x2 ms = st[s]; const v4u w = raw[i];
;             v2u lo, hi; lo.x = pk2((bflo(w.x) - ms.x) * ms.y * g0[0], (bfhi(w.x) - ms.x) * ms.y * g0[1]); lo.y = pk2((bflo(w.y) - ms.x) * ms.y * g0[2], (bfhi(w.y) - ms.x) * ms.y * g0[3]);
;             hi.x = pk2((bflo(w.z) - ms.x) * ms.y * g1[0], (bfhi(w.z) - ms.x) * ms.y * g1[1]); hi.y = pk2((bflo(w.w) - ms.x) * ms.y * g1[2], (bfhi(w.w) - ms.x) * ms.y * g1[3]);
;             *(LAS v2u*)(wl + s * VP2 + (4 * c16) * 2) = lo; *(LAS v2u*)(wl + s * VP2 + (16 + 4 * c16) * 2) = hi; }
	v_pk_add_f32 v[118:119], v[118:119], v[88:89] op_sel_hi:[1,0] neg_lo:[0,1] neg_hi:[0,1]
	v_pk_add_f32 v[112:113], v[112:113], v[88:89] op_sel_hi:[1,0] neg_lo:[0,1] neg_hi:[0,1]
	v_pk_mul_f32 v[118:119], v[88:89], v[118:119] op_sel:[1,0]
	v_pk_mul_f32 v[112:113], v[88:89], v[112:113] op_sel:[1,0]
	v_pk_mul_f32 v[118:119], v[116:117], v[118:119]
	v_pk_mul_f32 v[112:113], v[94:95], v[112:113]
	v_and_b32_sdwa v120, v119, v245 dst_sel:DWORD dst_unused:UNUSED_PAD src0_sel:WORD_1 src1_sel:DWORD
	v_and_b32_sdwa v121, v118, v245 dst_sel:DWORD dst_unused:UNUSED_PAD src0_sel:WORD_1 src1_sel:DWORD
	v_add3_u32 v118, v118, v121, s68
	v_add3_u32 v119, v119, v120, s68
	v_and_b32_sdwa v120, v113, v245 dst_sel:DWORD dst_unused:UNUSED_PAD src0_sel:WORD_1 src1_sel:DWORD
	v_and_b32_sdwa v121, v112, v245 dst_sel:DWORD dst_unused:UNUSED_PAD src0_sel:WORD_1 src1_sel:DWORD
	v_add3_u32 v113, v113, v120, s68
	v_add3_u32 v112, v112, v121, s68
	v_and_b32_e32 v113, 0xffff0000, v113
	v_and_b32_e32 v112, 0xffff0000, v112
	v_or_b32_sdwa v113, v113, v119 dst_sel:DWORD dst_unused:UNUSED_PAD src0_sel:DWORD src1_sel:WORD_1
	v_or_b32_sdwa v112, v112, v118 dst_sel:DWORD dst_unused:UNUSED_PAD src0_sel:DWORD src1_sel:WORD_1
	v_lshlrev_b32_e32 v119, 16, v115
	v_lshlrev_b32_e32 v118, 16, v114
	v_pk_add_f32 v[118:119], v[118:119], v[88:89] op_sel_hi:[1,0] neg_lo:[0,1] neg_hi:[0,1]
	v_and_b32_e32 v115, 0xffff0000, v115
	v_and_b32_e32 v114, 0xffff0000, v114
	v_pk_mul_f32 v[118:119], v[88:89], v[118:119] op_sel:[1,0]
	v_pk_add_f32 v[114:115], v[114:115], v[88:89] op_sel_hi:[1,0] neg_lo:[0,1] neg_hi:[0,1]
	v_pk_mul_f32 v[118:119], v[92:93], v[118:119]
	v_pk_mul_f32 v[88:89], v[88:89], v[114:115] op_sel:[1,0]
	v_and_b32_sdwa v114, v119, v245 dst_sel:DWORD dst_unused:UNUSED_PAD src0_sel:WORD_1 src1_sel:DWORD
	v_pk_mul_f32 v[88:89], v[90:91], v[88:89]
	v_and_b32_sdwa v115, v118, v245 dst_sel:DWORD dst_unused:UNUSED_PAD src0_sel:WORD_1 src1_sel:DWORD
	v_add3_u32 v115, v118, v115, s68
	v_add3_u32 v114, v119, v114, s68
	v_and_b32_sdwa v118, v89, v245 dst_sel:DWORD dst_unused:UNUSED_PAD src0_sel:WORD_1 src1_sel:DWORD
	v_and_b32_sdwa v119, v88, v245 dst_sel:DWORD dst_unused:UNUSED_PAD src0_sel:WORD_1 src1_sel:DWORD
	v_add3_u32 v89, v89, v118, s68
	v_add3_u32 v88, v88, v119, s68
	v_and_b32_e32 v89, 0xffff0000, v89
	v_and_b32_e32 v88, 0xffff0000, v88
	v_or_b32_sdwa v89, v89, v114 dst_sel:DWORD dst_unused:UNUSED_PAD src0_sel:DWORD src1_sel:WORD_1
	v_or_b32_sdwa v88, v88, v115 dst_sel:DWORD dst_unused:UNUSED_PAD src0_sel:DWORD src1_sel:WORD_1
	ds_write2_b64 v219, v[112:113], v[88:89] offset0:160 offset1:164
	ds_read_b64 v[112:113], v218 offset:10496
	v_lshlrev_b32_e32 v89, 16, v109
	v_lshlrev_b32_e32 v88, 16, v108
	v_and_b32_e32 v109, 0xffff0000, v109
	v_and_b32_e32 v108, 0xffff0000, v108
	s_waitcnt lgkmcnt(0)
	v_pk_add_f32 v[88:89], v[88:89], v[112:113] op_sel_hi:[1,0] neg_lo:[0,1] neg_hi:[0,1]
	v_pk_add_f32 v[108:109], v[108:109], v[112:113] op_sel_hi:[1,0] neg_lo:[0,1] neg_hi:[0,1]
	v_pk_mul_f32 v[88:89], v[112:113], v[88:89] op_sel:[1,0]
	v_pk_mul_f32 v[108:109], v[112:113], v[108:109] op_sel:[1,0]
	v_pk_mul_f32 v[88:89], v[116:117], v[88:89]
	v_pk_mul_f32 v[108:109], v[94:95], v[108:109]
	v_and_b32_sdwa v114, v89, v245 dst_sel:DWORD dst_unused:UNUSED_PAD src0_sel:WORD_1 src1_sel:DWORD
	v_and_b32_sdwa v115, v88, v245 dst_sel:DWORD dst_unused:UNUSED_PAD src0_sel:WORD_1 src1_sel:DWORD
	v_add3_u32 v88, v88, v115, s68
	v_add3_u32 v89, v89, v114, s68
	v_and_b32_sdwa v114, v109, v245 dst_sel:DWORD dst_unused:UNUSED_PAD src0_sel:WORD_1 src1_sel:DWORD
	v_and_b32_sdwa v115, v108, v245 dst_sel:DWORD dst_unused:UNUSED_PAD src0_sel:WORD_1 src1_sel:DWORD
	v_add3_u32 v109, v109, v114, s68
	v_add3_u32 v108, v108, v115, s68
	v_and_b32_e32 v109, 0xffff0000, v109
	v_and_b32_e32 v108, 0xffff0000, v108
	v_or_b32_sdwa v89, v109, v89 dst_sel:DWORD dst_unused:UNUSED_PAD src0_sel:DWORD src1_sel:WORD_1
	v_or_b32_sdwa v88, v108, v88 dst_sel:DWORD dst_unused:UNUSED_PAD src0_sel:DWORD src1_sel:WORD_1
	v_lshlrev_b32_e32 v109, 16, v111
	v_lshlrev_b32_e32 v108, 16, v110
	v_pk_add_f32 v[108:109], v[108:109], v[112:113] op_sel_hi:[1,0] neg_lo:[0,1] neg_hi:[0,1]
	v_and_b32_e32 v111, 0xffff0000, v111
	v_and_b32_e32 v110, 0xffff0000, v110
	v_pk_mul_f32 v[108:109], v[112:113], v[108:109] op_sel:[1,0]
	v_pk_add_f32 v[110:111], v[110:111], v[112:113] op_sel_hi:[1,0] neg_lo:[0,1] neg_hi:[0,1]
	v_pk_mul_f32 v[108:109], v[92:93], v[108:109]
	v_pk_mul_f32 v[110:111], v[112:113], v[110:111] op_sel:[1,0]
	v_and_b32_sdwa v112, v109, v245 dst_sel:DWORD dst_unused:UNUSED_PAD src0_sel:WORD_1 src1_sel:DWORD
	v_pk_mul_f32 v[110:111], v[90:91], v[110:111]
	v_and_b32_sdwa v113, v108, v245 dst_sel:DWORD dst_unused:UNUSED_PAD src0_sel:WORD_1 src1_sel:DWORD
	v_add3_u32 v108, v108, v113, s68
	v_add3_u32 v109, v109, v112, s68
	v_and_b32_sdwa v112, v111, v245 dst_sel:DWORD dst_unused:UNUSED_PAD src0_sel:WORD_1 src1_sel:DWORD
	v_and_b32_sdwa v113, v110, v245 dst_sel:DWORD dst_unused:UNUSED_PAD src0_sel:WORD_1 src1_sel:DWORD
	v_add3_u32 v111, v111, v112, s68
	v_add3_u32 v110, v110, v113, s68
	v_and_b32_e32 v111, 0xffff0000, v111
	v_and_b32_e32 v110, 0xffff0000, v110
	v_or_b32_sdwa v109, v111, v109 dst_sel:DWORD dst_unused:UNUSED_PAD src0_sel:DWORD src1_sel:WORD_1
	v_or_b32_sdwa v108, v110, v108 dst_sel:DWORD dst_unused:UNUSED_PAD src0_sel:DWORD src1_sel:WORD_1
	v_add_u32_e32 v110, 0x800, v219
	ds_write2_b64 v110, v[88:89], v[108:109] offset0:64 offset1:68
	ds_read_b64 v[88:89], v218 offset:10624
	v_lshlrev_b32_e32 v109, 16, v105
	v_lshlrev_b32_e32 v108, 16, v104
	v_and_b32_e32 v105, 0xffff0000, v105
	v_and_b32_e32 v104, 0xffff0000, v104
	s_waitcnt lgkmcnt(0)
; #define LAS __attribute__((address_space(3)))
; __device__ __forceinline__ unsigned pk2(float lo, float hi) { return f2bf(lo) | (f2bf(hi) << 16); }
; __device__ __forceinline__ float bflo(unsigned w) { return __uint_as_float(w << 16); }
; __device__ __forceinline__ float bfhi(unsigned w) { return __uint_as_float(w & 0xffff0000u); }
; __device__ __forceinline__ void sgu_item(LAS unsigned char* wl, const bf16* proj, bf16* ymix, const float* vstat, const float* sgu_g, const bf16* Wm, const float* sgu_b, int chunk, int h, int lane) {
;     ...
;         for (int i = 0; i < 8; ++i) { const int s = rsub + 16 * i; const f32x2 ms = st[s]; const v4u w = raw[i];
;             v2u lo, hi; lo.x = pk2((bflo(w.x) - ms.x) * ms.y * g0[0], (bfhi(w.x) - ms.x) * ms.y * g0[1]); lo.y = pk2((bflo(w.y) - ms.x) * ms.y * g0[2], (bfhi(w.y) - ms.x) * ms.y * g0[3]);
;             hi.x = pk2((bflo(w.z) - ms.x) * ms.y * g1[0], (bfhi(w.z) - ms.x) * ms.y * g1[1]); hi.y = pk2((bflo(w.w) - ms.x) * ms.y * g1[2], (bfhi(w.w) - ms.x) * ms.y * g1[3]);
;             *(LAS v2u*)(wl + s * VP2 + (4 * c16) * 2) = lo; *(LAS v2u*)(wl + s * VP2 + (16 + 4 * c16) * 2) = hi; }
	v_pk_add_f32 v[108:109], v[108:109], v[88:89] op_sel_hi:[1,0] neg_lo:[0,1] neg_hi:[0,1]
	v_pk_add_f32 v[104:105], v[104:105], v[88:89] op_sel_hi:[1,0] neg_lo:[0,1] neg_hi:[0,1]
	v_pk_mul_f32 v[108:109], v[88:89], v[108:109] op_sel:[1,0]
	v_pk_mul_f32 v[104:105], v[88:89], v[104:105] op_sel:[1,0]
	v_pk_mul_f32 v[108:109], v[116:117], v[108:109]
	v_pk_mul_f32 v[104:105], v[94:95], v[104:105]
	v_and_b32_sdwa v111, v109, v245 dst_sel:DWORD dst_unused:UNUSED_PAD src0_sel:WORD_1 src1_sel:DWORD
	v_and_b32_sdwa v112, v108, v245 dst_sel:DWORD dst_unused:UNUSED_PAD src0_sel:WORD_1 src1_sel:DWORD
	v_add3_u32 v108, v108, v112, s68
	v_add3_u32 v109, v109, v111, s68
	v_and_b32_sdwa v111, v105, v245 dst_sel:DWORD dst_unused:UNUSED_PAD src0_sel:WORD_1 src1_sel:DWORD
	v_and_b32_sdwa v112, v104, v245 dst_sel:DWORD dst_unused:UNUSED_PAD src0_sel:WORD_1 src1_sel:DWORD
	v_add3_u32 v105, v105, v111, s68
	v_add3_u32 v104, v104, v112, s68
	v_and_b32_e32 v105, 0xffff0000, v105
	v_and_b32_e32 v104, 0xffff0000, v104
	v_or_b32_sdwa v105, v105, v109 dst_sel:DWORD dst_unused:UNUSED_PAD src0_sel:DWORD src1_sel:WORD_1
	v_or_b32_sdwa v104, v104, v108 dst_sel:DWORD dst_unused:UNUSED_PAD src0_sel:DWORD src1_sel:WORD_1
	v_lshlrev_b32_e32 v109, 16, v107
	v_lshlrev_b32_e32 v108, 16, v106
	v_pk_add_f32 v[108:109], v[108:109], v[88:89] op_sel_hi:[1,0] neg_lo:[0,1] neg_hi:[0,1]
	v_and_b32_e32 v107, 0xffff0000, v107
	v_and_b32_e32 v106, 0xffff0000, v106
	v_pk_mul_f32 v[108:109], v[88:89], v[108:109] op_sel:[1,0]
	v_pk_add_f32 v[106:107], v[106:107], v[88:89] op_sel_hi:[1,0] neg_lo:[0,1] neg_hi:[0,1]
	v_pk_mul_f32 v[108:109], v[92:93], v[108:109]
	v_pk_mul_f32 v[88:89], v[88:89], v[106:107] op_sel:[1,0]
	v_and_b32_sdwa v106, v109, v245 dst_sel:DWORD dst_unused:UNUSED_PAD src0_sel:WORD_1 src1_sel:DWORD
	v_pk_mul_f32 v[88:89], v[90:91], v[88:89]
	v_and_b32_sdwa v107, v108, v245 dst_sel:DWORD dst_unused:UNUSED_PAD src0_sel:WORD_1 src1_sel:DWORD
	v_add3_u32 v107, v108, v107, s68
	v_add3_u32 v106, v109, v106, s68
	v_and_b32_sdwa v108, v89, v245 dst_sel:DWORD dst_unused:UNUSED_PAD src0_sel:WORD_1 src1_sel:DWORD
	v_and_b32_sdwa v109, v88, v245 dst_sel:DWORD dst_unused:UNUSED_PAD src0_sel:WORD_1 src1_sel:DWORD
	v_add3_u32 v89, v89, v108, s68
	v_add3_u32 v88, v88, v109, s68
	v_and_b32_e32 v89, 0xffff0000, v89
	v_and_b32_e32 v88, 0xffff0000, v88
	v_or_b32_sdwa v89, v89, v106 dst_sel:DWORD dst_unused:UNUSED_PAD src0_sel:DWORD src1_sel:WORD_1
	v_or_b32_sdwa v88, v88, v107 dst_sel:DWORD dst_unused:UNUSED_PAD src0_sel:DWORD src1_sel:WORD_1
	ds_write2_b64 v110, v[104:105], v[88:89] offset0:224 offset1:228
	ds_read_b64 v[104:105], v218 offset:10752
	v_lshlrev_b32_e32 v89, 16, v101
	v_lshlrev_b32_e32 v88, 16, v100
	v_and_b32_e32 v101, 0xffff0000, v101
	v_and_b32_e32 v100, 0xffff0000, v100
	s_waitcnt lgkmcnt(0)
	v_pk_add_f32 v[88:89], v[88:89], v[104:105] op_sel_hi:[1,0] neg_lo:[0,1] neg_hi:[0,1]
	v_pk_add_f32 v[100:101], v[100:101], v[104:105] op_sel_hi:[1,0] neg_lo:[0,1] neg_hi:[0,1]
	v_pk_mul_f32 v[88:89], v[104:105], v[88:89] op_sel:[1,0]
	v_pk_mul_f32 v[100:101], v[104:105], v[100:101] op_sel:[1,0]
	v_pk_mul_f32 v[88:89], v[116:117], v[88:89]
	v_pk_mul_f32 v[100:101], v[94:95], v[100:101]
	v_and_b32_sdwa v106, v89, v245 dst_sel:DWORD dst_unused:UNUSED_PAD src0_sel:WORD_1 src1_sel:DWORD
	v_and_b32_sdwa v107, v88, v245 dst_sel:DWORD dst_unused:UNUSED_PAD src0_sel:WORD_1 src1_sel:DWORD
	v_add3_u32 v88, v88, v107, s68
	v_add3_u32 v89, v89, v106, s68
	v_and_b32_sdwa v106, v101, v245 dst_sel:DWORD dst_unused:UNUSED_PAD src0_sel:WORD_1 src1_sel:DWORD
	v_and_b32_sdwa v107, v100, v245 dst_sel:DWORD dst_unused:UNUSED_PAD src0_sel:WORD_1 src1_sel:DWORD
	v_add3_u32 v101, v101, v106, s68
	v_add3_u32 v100, v100, v107, s68
	v_and_b32_e32 v101, 0xffff0000, v101
	v_and_b32_e32 v100, 0xffff0000, v100
	v_or_b32_sdwa v89, v101, v89 dst_sel:DWORD dst_unused:UNUSED_PAD src0_sel:DWORD src1_sel:WORD_1
	v_or_b32_sdwa v88, v100, v88 dst_sel:DWORD dst_unused:UNUSED_PAD src0_sel:DWORD src1_sel:WORD_1
	v_lshlrev_b32_e32 v101, 16, v103
	v_lshlrev_b32_e32 v100, 16, v102
	v_pk_add_f32 v[100:101], v[100:101], v[104:105] op_sel_hi:[1,0] neg_lo:[0,1] neg_hi:[0,1]
	v_and_b32_e32 v103, 0xffff0000, v103
	v_and_b32_e32 v102, 0xffff0000, v102
	v_pk_mul_f32 v[100:101], v[104:105], v[100:101] op_sel:[1,0]
	v_pk_add_f32 v[102:103], v[102:103], v[104:105] op_sel_hi:[1,0] neg_lo:[0,1] neg_hi:[0,1]
	v_pk_mul_f32 v[100:101], v[92:93], v[100:101]
	v_pk_mul_f32 v[102:103], v[104:105], v[102:103] op_sel:[1,0]
	v_and_b32_sdwa v104, v101, v245 dst_sel:DWORD dst_unused:UNUSED_PAD src0_sel:WORD_1 src1_sel:DWORD
	v_pk_mul_f32 v[102:103], v[90:91], v[102:103]
	v_and_b32_sdwa v105, v100, v245 dst_sel:DWORD dst_unused:UNUSED_PAD src0_sel:WORD_1 src1_sel:DWORD
	v_add3_u32 v100, v100, v105, s68
	v_add3_u32 v101, v101, v104, s68
	v_and_b32_sdwa v104, v103, v245 dst_sel:DWORD dst_unused:UNUSED_PAD src0_sel:WORD_1 src1_sel:DWORD
	v_and_b32_sdwa v105, v102, v245 dst_sel:DWORD dst_unused:UNUSED_PAD src0_sel:WORD_1 src1_sel:DWORD
	v_add3_u32 v103, v103, v104, s68
	v_add3_u32 v102, v102, v105, s68
	v_and_b32_e32 v103, 0xffff0000, v103
	v_and_b32_e32 v102, 0xffff0000, v102
	v_or_b32_sdwa v101, v103, v101 dst_sel:DWORD dst_unused:UNUSED_PAD src0_sel:DWORD src1_sel:WORD_1
	v_or_b32_sdwa v100, v102, v100 dst_sel:DWORD dst_unused:UNUSED_PAD src0_sel:DWORD src1_sel:WORD_1
	v_add_u32_e32 v102, 0x1000, v219
	ds_write2_b64 v102, v[88:89], v[100:101] offset0:128 offset1:132
	ds_read_b64 v[88:89], v218 offset:10880
	v_lshlrev_b32_e32 v101, 16, v97
	v_lshlrev_b32_e32 v100, 16, v96
	v_and_b32_e32 v97, 0xffff0000, v97
	v_and_b32_e32 v96, 0xffff0000, v96
	s_waitcnt lgkmcnt(0)
; #define LAS __attribute__((address_space(3)))
; __device__ __forceinline__ unsigned pk2(float lo, float hi) { return f2bf(lo) | (f2bf(hi) << 16); }
; __device__ __forceinline__ float bflo(unsigned w) { return __uint_as_float(w << 16); }
; __device__ __forceinline__ float bfhi(unsigned w) { return __uint_as_float(w & 0xffff0000u); }
; __device__ __forceinline__ void sgu_item(LAS unsigned char* wl, const bf16* proj, bf16* ymix, const float* vstat, const float* sgu_g, const bf16* Wm, const float* sgu_b, int chunk, int h, int lane) {
;     ...
;         for (int i = 0; i < 8; ++i) { const int s = rsub + 16 * i; const f32x2 ms = st[s]; const v4u w = raw[i];
;             v2u lo, hi; lo.x = pk2((bflo(w.x) - ms.x) * ms.y * g0[0], (bfhi(w.x) - ms.x) * ms.y * g0[1]); lo.y = pk2((bflo(w.y) - ms.x) * ms.y * g0[2], (bfhi(w.y) - ms.x) * ms.y * g0[3]);
;             hi.x = pk2((bflo(w.z) - ms.x) * ms.y * g1[0], (bfhi(w.z) - ms.x) * ms.y * g1[1]); hi.y = pk2((bflo(w.w) - ms.x) * ms.y * g1[2], (bfhi(w.w) - ms.x) * ms.y * g1[3]);
;             *(LAS v2u*)(wl + s * VP2 + (4 * c16) * 2) = lo; *(LAS v2u*)(wl + s * VP2 + (16 + 4 * c16) * 2) = hi; }
	v_pk_add_f32 v[100:101], v[100:101], v[88:89] op_sel_hi:[1,0] neg_lo:[0,1] neg_hi:[0,1]
	v_pk_add_f32 v[96:97], v[96:97], v[88:89] op_sel_hi:[1,0] neg_lo:[0,1] neg_hi:[0,1]
	v_pk_mul_f32 v[100:101], v[88:89], v[100:101] op_sel:[1,0]
	v_pk_mul_f32 v[96:97], v[88:89], v[96:97] op_sel:[1,0]
	v_pk_mul_f32 v[100:101], v[116:117], v[100:101]
	v_pk_mul_f32 v[96:97], v[94:95], v[96:97]
	v_and_b32_sdwa v102, v101, v245 dst_sel:DWORD dst_unused:UNUSED_PAD src0_sel:WORD_1 src1_sel:DWORD
	v_and_b32_sdwa v103, v100, v245 dst_sel:DWORD dst_unused:UNUSED_PAD src0_sel:WORD_1 src1_sel:DWORD
	v_add3_u32 v100, v100, v103, s68
	v_add3_u32 v101, v101, v102, s68
	v_and_b32_sdwa v102, v97, v245 dst_sel:DWORD dst_unused:UNUSED_PAD src0_sel:WORD_1 src1_sel:DWORD
	v_and_b32_sdwa v103, v96, v245 dst_sel:DWORD dst_unused:UNUSED_PAD src0_sel:WORD_1 src1_sel:DWORD
	v_add3_u32 v97, v97, v102, s68
	v_add3_u32 v96, v96, v103, s68
	v_and_b32_e32 v97, 0xffff0000, v97
	v_and_b32_e32 v96, 0xffff0000, v96
	v_or_b32_sdwa v97, v97, v101 dst_sel:DWORD dst_unused:UNUSED_PAD src0_sel:DWORD src1_sel:WORD_1
	v_or_b32_sdwa v96, v96, v100 dst_sel:DWORD dst_unused:UNUSED_PAD src0_sel:DWORD src1_sel:WORD_1
	v_lshlrev_b32_e32 v101, 16, v99
	v_lshlrev_b32_e32 v100, 16, v98
	v_pk_add_f32 v[100:101], v[100:101], v[88:89] op_sel_hi:[1,0] neg_lo:[0,1] neg_hi:[0,1]
	v_and_b32_e32 v99, 0xffff0000, v99
	v_and_b32_e32 v98, 0xffff0000, v98
	v_pk_mul_f32 v[100:101], v[88:89], v[100:101] op_sel:[1,0]
	v_pk_add_f32 v[98:99], v[98:99], v[88:89] op_sel_hi:[1,0] neg_lo:[0,1] neg_hi:[0,1]
	v_pk_mul_f32 v[100:101], v[92:93], v[100:101]
	v_pk_mul_f32 v[88:89], v[88:89], v[98:99] op_sel:[1,0]
	v_and_b32_sdwa v98, v101, v245 dst_sel:DWORD dst_unused:UNUSED_PAD src0_sel:WORD_1 src1_sel:DWORD
	v_pk_mul_f32 v[88:89], v[90:91], v[88:89]
	v_and_b32_sdwa v99, v100, v245 dst_sel:DWORD dst_unused:UNUSED_PAD src0_sel:WORD_1 src1_sel:DWORD
	v_add3_u32 v99, v100, v99, s68
	v_add3_u32 v98, v101, v98, s68
	v_and_b32_sdwa v100, v89, v245 dst_sel:DWORD dst_unused:UNUSED_PAD src0_sel:WORD_1 src1_sel:DWORD
	v_and_b32_sdwa v101, v88, v245 dst_sel:DWORD dst_unused:UNUSED_PAD src0_sel:WORD_1 src1_sel:DWORD
	v_add3_u32 v89, v89, v100, s68
	v_add3_u32 v88, v88, v101, s68
	v_and_b32_e32 v89, 0xffff0000, v89
	v_and_b32_e32 v88, 0xffff0000, v88
	v_or_b32_sdwa v89, v89, v98 dst_sel:DWORD dst_unused:UNUSED_PAD src0_sel:DWORD src1_sel:WORD_1
	v_or_b32_sdwa v88, v88, v99 dst_sel:DWORD dst_unused:UNUSED_PAD src0_sel:DWORD src1_sel:WORD_1
	v_add_u32_e32 v98, 0x1800, v219
	ds_write2_b64 v98, v[96:97], v[88:89] offset0:32 offset1:36
	ds_read_b64 v[88:89], v218 offset:11008
	v_lshlrev_b32_e32 v97, 16, v85
	v_lshlrev_b32_e32 v96, 16, v84
	v_and_b32_e32 v85, 0xffff0000, v85
	v_and_b32_e32 v84, 0xffff0000, v84
	s_waitcnt lgkmcnt(0)
	v_pk_add_f32 v[96:97], v[96:97], v[88:89] op_sel_hi:[1,0] neg_lo:[0,1] neg_hi:[0,1]
	v_pk_add_f32 v[84:85], v[84:85], v[88:89] op_sel_hi:[1,0] neg_lo:[0,1] neg_hi:[0,1]
	v_pk_mul_f32 v[96:97], v[88:89], v[96:97] op_sel:[1,0]
	v_pk_mul_f32 v[84:85], v[88:89], v[84:85] op_sel:[1,0]
	v_pk_mul_f32 v[96:97], v[116:117], v[96:97]
	v_pk_mul_f32 v[84:85], v[94:95], v[84:85]
	v_and_b32_sdwa v99, v97, v245 dst_sel:DWORD dst_unused:UNUSED_PAD src0_sel:WORD_1 src1_sel:DWORD
	v_and_b32_sdwa v100, v96, v245 dst_sel:DWORD dst_unused:UNUSED_PAD src0_sel:WORD_1 src1_sel:DWORD
	v_add3_u32 v96, v96, v100, s68
	v_add3_u32 v97, v97, v99, s68
	v_and_b32_sdwa v99, v85, v245 dst_sel:DWORD dst_unused:UNUSED_PAD src0_sel:WORD_1 src1_sel:DWORD
	v_and_b32_sdwa v100, v84, v245 dst_sel:DWORD dst_unused:UNUSED_PAD src0_sel:WORD_1 src1_sel:DWORD
	v_add3_u32 v85, v85, v99, s68
	v_add3_u32 v84, v84, v100, s68
	v_and_b32_e32 v85, 0xffff0000, v85
	v_and_b32_e32 v84, 0xffff0000, v84
	v_or_b32_sdwa v85, v85, v97 dst_sel:DWORD dst_unused:UNUSED_PAD src0_sel:DWORD src1_sel:WORD_1
	v_or_b32_sdwa v84, v84, v96 dst_sel:DWORD dst_unused:UNUSED_PAD src0_sel:DWORD src1_sel:WORD_1
	v_lshlrev_b32_e32 v97, 16, v87
	v_lshlrev_b32_e32 v96, 16, v86
	v_pk_add_f32 v[96:97], v[96:97], v[88:89] op_sel_hi:[1,0] neg_lo:[0,1] neg_hi:[0,1]
	v_and_b32_e32 v87, 0xffff0000, v87
	v_and_b32_e32 v86, 0xffff0000, v86
	v_pk_mul_f32 v[96:97], v[88:89], v[96:97] op_sel:[1,0]
	v_pk_add_f32 v[86:87], v[86:87], v[88:89] op_sel_hi:[1,0] neg_lo:[0,1] neg_hi:[0,1]
	v_pk_mul_f32 v[96:97], v[92:93], v[96:97]
	v_pk_mul_f32 v[86:87], v[88:89], v[86:87] op_sel:[1,0]
	v_and_b32_sdwa v88, v97, v245 dst_sel:DWORD dst_unused:UNUSED_PAD src0_sel:WORD_1 src1_sel:DWORD
	v_pk_mul_f32 v[86:87], v[90:91], v[86:87]
	v_and_b32_sdwa v89, v96, v245 dst_sel:DWORD dst_unused:UNUSED_PAD src0_sel:WORD_1 src1_sel:DWORD
	v_add3_u32 v89, v96, v89, s68
	v_add3_u32 v88, v97, v88, s68
	v_and_b32_sdwa v96, v87, v245 dst_sel:DWORD dst_unused:UNUSED_PAD src0_sel:WORD_1 src1_sel:DWORD
	v_and_b32_sdwa v97, v86, v245 dst_sel:DWORD dst_unused:UNUSED_PAD src0_sel:WORD_1 src1_sel:DWORD
	v_add3_u32 v87, v87, v96, s68
	v_add3_u32 v86, v86, v97, s68
	v_and_b32_e32 v87, 0xffff0000, v87
	v_and_b32_e32 v86, 0xffff0000, v86
	v_or_b32_sdwa v87, v87, v88 dst_sel:DWORD dst_unused:UNUSED_PAD src0_sel:DWORD src1_sel:WORD_1
	v_or_b32_sdwa v86, v86, v89 dst_sel:DWORD dst_unused:UNUSED_PAD src0_sel:DWORD src1_sel:WORD_1
	ds_write2_b64 v98, v[84:85], v[86:87] offset0:192 offset1:196
	ds_read_b64 v[84:85], v218 offset:11136
	v_lshlrev_b32_e32 v87, 16, v81
	v_lshlrev_b32_e32 v86, 16, v80
	v_and_b32_e32 v81, 0xffff0000, v81
	v_and_b32_e32 v80, 0xffff0000, v80
	s_waitcnt lgkmcnt(0)
; #define LAS __attribute__((address_space(3)))
; #define MFMA16(a, b, c) __builtin_amdgcn_mfma_f32_16x16x32_bf16((a), (b), (c), 0, 0, 0)
; __device__ __forceinline__ unsigned pk2(float lo, float hi) { return f2bf(lo) | (f2bf(hi) << 16); }
; __device__ __forceinline__ float bflo(unsigned w) { return __uint_as_float(w << 16); }
; __device__ __forceinline__ float bfhi(unsigned w) { return __uint_as_float(w & 0xffff0000u); }
; #define LDS_WAIT() asm volatile("s_waitcnt lgkmcnt(0)" ::: "memory")
; __device__ __forceinline__ void sgu_item(LAS unsigned char* wl, const bf16* proj, bf16* ymix, const float* vstat, const float* sgu_g, const bf16* Wm, const float* sgu_b, int chunk, int h, int lane) {
;     ...
;         for (int i = 0; i < 8; ++i) { const int s = rsub + 16 * i; const f32x2 ms = st[s]; const v4u w = raw[i];
;             v2u lo, hi; lo.x = pk2((bflo(w.x) - ms.x) * ms.y * g0[0], (bfhi(w.x) - ms.x) * ms.y * g0[1]); lo.y = pk2((bflo(w.y) - ms.x) * ms.y * g0[2], (bfhi(w.y) - ms.x) * ms.y * g0[3]);
;             hi.x = pk2((bflo(w.z) - ms.x) * ms.y * g1[0], (bfhi(w.z) - ms.x) * ms.y * g1[1]); hi.y = pk2((bflo(w.w) - ms.x) * ms.y * g1[2], (bfhi(w.w) - ms.x) * ms.y * g1[3]);
;             *(LAS v2u*)(wl + s * VP2 + (4 * c16) * 2) = lo; *(LAS v2u*)(wl + s * VP2 + (16 + 4 * c16) * 2) = hi; }
;         v4u uu8[8];
; #pragma unroll
;         for (int tb = 0; tb < 8; ++tb) uu8[tb] = __builtin_nontemporal_load((const v4u*)(proj + (R0 + 16 * tb + r) * DIN + 512 + colv + 8 * q));
;         LDS_WAIT();
;         v2u olo[8];
; #pragma unroll
;         for (int n = 0; n < 2; ++n) {
;             f32x4 z[8];
; #pragma unroll
;             for (int tb = 0; tb < 8; ++tb) z[tb] = (f32x4){0.f, 0.f, 0.f, 0.f};
;             int f = 0;
; #pragma unroll
;             for (int ks = 0; ks < 4; ++ks) {
;                 LAS unsigned char* ad = wl + (ks * 32 + 8 * q + (r >> 2)) * VP2 + (16 * n) * 2 + 8 * (r & 3);
;                 const s16x4 lo = __builtin_bit_cast(s16x4, __builtin_amdgcn_ds_read_tr16_b64_v4i16((LAS s16x4*)ad));
;                 const s16x4 hi = __builtin_bit_cast(s16x4, __builtin_amdgcn_ds_read_tr16_b64_v4i16((LAS s16x4*)(ad + 4 * VP2)));
;                 const bf16x8 vf = __builtin_shufflevector(lo, hi, 0, 1, 2, 3, 4, 5, 6, 7);
; #pragma unroll
;                 for (int tb = 2 * ks; tb < 8; ++tb) z[tb] = MFMA16(vf, wmf[f++], z[tb]);
	v_pk_add_f32 v[86:87], v[86:87], v[84:85] op_sel_hi:[1,0] neg_lo:[0,1] neg_hi:[0,1]
	v_pk_add_f32 v[80:81], v[80:81], v[84:85] op_sel_hi:[1,0] neg_lo:[0,1] neg_hi:[0,1]
	v_pk_mul_f32 v[86:87], v[84:85], v[86:87] op_sel:[1,0]
	v_pk_mul_f32 v[80:81], v[84:85], v[80:81] op_sel:[1,0]
	v_pk_mul_f32 v[86:87], v[116:117], v[86:87]
	v_pk_mul_f32 v[80:81], v[94:95], v[80:81]
	v_and_b32_sdwa v88, v87, v245 dst_sel:DWORD dst_unused:UNUSED_PAD src0_sel:WORD_1 src1_sel:DWORD
	v_and_b32_sdwa v89, v86, v245 dst_sel:DWORD dst_unused:UNUSED_PAD src0_sel:WORD_1 src1_sel:DWORD
	v_add3_u32 v86, v86, v89, s68
	v_add3_u32 v87, v87, v88, s68
	v_and_b32_sdwa v88, v81, v245 dst_sel:DWORD dst_unused:UNUSED_PAD src0_sel:WORD_1 src1_sel:DWORD
	v_and_b32_sdwa v89, v80, v245 dst_sel:DWORD dst_unused:UNUSED_PAD src0_sel:WORD_1 src1_sel:DWORD
	v_add3_u32 v81, v81, v88, s68
	v_add3_u32 v80, v80, v89, s68
	v_and_b32_e32 v81, 0xffff0000, v81
	v_and_b32_e32 v80, 0xffff0000, v80
	v_or_b32_sdwa v81, v81, v87 dst_sel:DWORD dst_unused:UNUSED_PAD src0_sel:DWORD src1_sel:WORD_1
	v_or_b32_sdwa v80, v80, v86 dst_sel:DWORD dst_unused:UNUSED_PAD src0_sel:DWORD src1_sel:WORD_1
	v_lshlrev_b32_e32 v87, 16, v83
	v_lshlrev_b32_e32 v86, 16, v82
	v_pk_add_f32 v[86:87], v[86:87], v[84:85] op_sel_hi:[1,0] neg_lo:[0,1] neg_hi:[0,1]
	v_and_b32_e32 v83, 0xffff0000, v83
	v_and_b32_e32 v82, 0xffff0000, v82
	v_pk_mul_f32 v[86:87], v[84:85], v[86:87] op_sel:[1,0]
	v_pk_add_f32 v[82:83], v[82:83], v[84:85] op_sel_hi:[1,0] neg_lo:[0,1] neg_hi:[0,1]
	v_pk_mul_f32 v[86:87], v[92:93], v[86:87]
	v_pk_mul_f32 v[82:83], v[84:85], v[82:83] op_sel:[1,0]
	v_and_b32_sdwa v84, v87, v245 dst_sel:DWORD dst_unused:UNUSED_PAD src0_sel:WORD_1 src1_sel:DWORD
	v_pk_mul_f32 v[82:83], v[90:91], v[82:83]
	v_and_b32_sdwa v85, v86, v245 dst_sel:DWORD dst_unused:UNUSED_PAD src0_sel:WORD_1 src1_sel:DWORD
	v_add3_u32 v85, v86, v85, s68
	v_add3_u32 v84, v87, v84, s68
	v_and_b32_sdwa v86, v83, v245 dst_sel:DWORD dst_unused:UNUSED_PAD src0_sel:WORD_1 src1_sel:DWORD
	v_and_b32_sdwa v87, v82, v245 dst_sel:DWORD dst_unused:UNUSED_PAD src0_sel:WORD_1 src1_sel:DWORD
	v_add3_u32 v83, v83, v86, s68
	v_add3_u32 v82, v82, v87, s68
	v_and_b32_e32 v83, 0xffff0000, v83
	v_and_b32_e32 v82, 0xffff0000, v82
	v_or_b32_sdwa v83, v83, v84 dst_sel:DWORD dst_unused:UNUSED_PAD src0_sel:DWORD src1_sel:WORD_1
	v_or_b32_sdwa v82, v82, v85 dst_sel:DWORD dst_unused:UNUSED_PAD src0_sel:DWORD src1_sel:WORD_1
	v_add_u32_e32 v84, 0x2000, v219
	ds_write2_b64 v84, v[80:81], v[82:83] offset0:96 offset1:100
	v_lshl_add_u64 v[80:81], v[188:189], 0, s[20:21]
	v_add_co_u32_e32 v82, vcc, s0, v80
	s_mov_b32 s0, 0xf10c000
	s_nop 0
	v_addc_co_u32_e32 v83, vcc, 0, v81, vcc
	global_load_dwordx4 v[104:107], v[82:83], off offset:1024 nt
	v_add_co_u32_e32 v82, vcc, s0, v80
	s_mov_b32 s0, 0xf118000
	s_nop 0
	v_addc_co_u32_e32 v83, vcc, 0, v81, vcc
	global_load_dwordx4 v[100:103], v[82:83], off offset:1024 nt
	v_add_co_u32_e32 v82, vcc, s0, v80
	s_mov_b32 s0, 0xf130000
	s_nop 0
	v_addc_co_u32_e32 v83, vcc, 0, v81, vcc
	global_load_dwordx4 v[96:99], v[82:83], off offset:1024 nt
	v_lshl_add_u64 v[82:83], v[190:191], 0, s[20:21]
	global_load_dwordx4 v[92:95], v[82:83], off nt
	v_add_co_u32_e32 v82, vcc, s0, v80
	s_mov_b32 s0, 0xf13c000
	s_nop 0
	v_addc_co_u32_e32 v83, vcc, 0, v81, vcc
	global_load_dwordx4 v[88:91], v[82:83], off offset:1024 nt
	v_add_co_u32_e32 v82, vcc, s0, v80
	s_mov_b32 s0, 0xf148000
	s_nop 0
	v_addc_co_u32_e32 v83, vcc, 0, v81, vcc
	global_load_dwordx4 v[84:87], v[82:83], off offset:1024 nt
	v_add_co_u32_e32 v80, vcc, s0, v80
	v_lshl_add_u64 v[108:109], v[186:187], 0, s[20:21]
	s_nop 0
	v_addc_co_u32_e32 v81, vcc, 0, v81, vcc
	global_load_dwordx4 v[80:83], v[80:81], off offset:1024 nt
	s_mov_b32 s0, 0x10900000
	global_load_dwordx4 v[108:111], v[108:109], off nt
	s_waitcnt lgkmcnt(0)
	ds_read_b64_tr_b16 v[116:117], v220 offset:320
	ds_read_b64_tr_b16 v[114:115], v220
	ds_read_b64_tr_b16 v[112:113], v220 offset:32
	ds_read_b64_tr_b16 v[208:209], v220 offset:2560
	ds_read_b64_tr_b16 v[210:211], v220 offset:2880
	s_waitcnt lgkmcnt(0)
	v_mfma_f32_16x16x32_bf16 v[118:121], v[114:117], v[0:3], 0
	v_mfma_f32_16x16x32_bf16 v[122:125], v[114:117], v[4:7], 0
	s_nop 6
	v_mov_b32_e32 v138, v119
	v_mov_b32_e32 v119, v120
	v_pk_add_f32 v[118:119], v[162:163], v[118:119]
	v_mfma_f32_16x16x32_bf16 v[126:129], v[114:117], v[8:11], 0
	v_mov_b32_e32 v139, v121
	v_pk_add_f32 v[138:139], v[162:163], v[138:139]
	v_mfma_f32_16x16x32_bf16 v[130:133], v[114:117], v[16:19], 0
	v_mfma_f32_16x16x32_bf16 v[134:137], v[114:117], v[24:27], 0
	v_mfma_f32_16x16x32_bf16 v[200:203], v[114:117], v[48:51], 0
	v_mfma_f32_16x16x32_bf16 v[204:207], v[114:117], v[32:35], 0
	v_mfma_f32_16x16x32_bf16 v[114:117], v[114:117], v[40:43], 0
	v_mfma_f32_16x16x32_bf16 v[126:129], v[208:211], v[12:15], v[126:129]
	v_mfma_f32_16x16x32_bf16 v[130:133], v[208:211], v[20:23], v[130:133]
	v_mfma_f32_16x16x32_bf16 v[134:137], v[208:211], v[28:31], v[134:137]
	v_mfma_f32_16x16x32_bf16 v[200:203], v[208:211], v[56:59], v[200:203]
	v_mfma_f32_16x16x32_bf16 v[204:207], v[208:211], v[36:39], v[204:207]
	v_mfma_f32_16x16x32_bf16 v[114:117], v[208:211], v[44:47], v[114:117]
	ds_read_b64_tr_b16 v[208:209], v220 offset:5120
	ds_read_b64_tr_b16 v[210:211], v220 offset:5440
	s_waitcnt lgkmcnt(0)
	v_mfma_f32_16x16x32_bf16 v[222:225], v[208:211], v[60:63], v[200:203]
	v_mfma_f32_16x16x32_bf16 v[200:203], v[208:211], v[64:67], v[204:207]
	s_nop 2
	ds_read_b64_tr_b16 v[204:205], v220 offset:7680
	ds_read_b64_tr_b16 v[206:207], v220 offset:8000
	s_waitcnt lgkmcnt(0)
	v_mfma_f32_16x16x32_bf16 v[226:229], v[204:207], v[68:71], v[200:203]
	s_waitcnt vmcnt(0)
; #define MFMA16(a, b, c) __builtin_amdgcn_mfma_f32_16x16x32_bf16((a), (b), (c), 0, 0, 0)
; __device__ __forceinline__ unsigned pk2(float lo, float hi) { return f2bf(lo) | (f2bf(hi) << 16); }
; __device__ __forceinline__ float bflo(unsigned w) { return __uint_as_float(w << 16); }
; __device__ __forceinline__ float bfhi(unsigned w) { return __uint_as_float(w & 0xffff0000u); }
; __device__ __forceinline__ void sgu_item(LAS unsigned char* wl, const bf16* proj, bf16* ymix, const float* vstat, const float* sgu_g, const bf16* Wm, const float* sgu_b, int chunk, int h, int lane) {
;     ...
;                 for (int tb = 2 * ks; tb < 8; ++tb) z[tb] = MFMA16(vf, wmf[f++], z[tb]);
;             }
; #pragma unroll
;             for (int tb = 0; tb < 8; ++tb) { const v4u uu = uu8[tb]; const unsigned ux = n == 0 ? uu.x : uu.z, uy = n == 0 ? uu.y : uu.w;
;                 v2u o; o.x = pk2(bflo(ux) * (z[tb][0] + bias[tb]), bfhi(ux) * (z[tb][1] + bias[tb])); o.y = pk2(bflo(uy) * (z[tb][2] + bias[tb]), bfhi(uy) * (z[tb][3] + bias[tb]));
;                 if (n == 0) olo[tb] = o;
	s_nop 1
	v_and_b32_e32 v201, 0xffff0000, v105
	v_and_b32_e32 v200, 0xffff0000, v104
	v_lshlrev_b32_e32 v105, 16, v105
	v_lshlrev_b32_e32 v104, 16, v104
	v_pk_mul_f32 v[214:215], v[118:119], v[104:105]
	v_mov_b32_e32 v104, v123
	v_mov_b32_e32 v105, v125
	v_pk_add_f32 v[104:105], v[164:165], v[104:105]
	v_and_b32_e32 v119, 0xffff0000, v101
	v_and_b32_e32 v118, 0xffff0000, v100
	v_mov_b32_e32 v123, v124
	v_mfma_f32_16x16x32_bf16 v[114:117], v[208:211], v[72:75], v[114:117]
	v_mul_f32_e64 v212, v104, v118
	v_mul_f32_e64 v213, v105, v119
	v_pk_add_f32 v[104:105], v[164:165], v[122:123]
	v_lshlrev_b32_e32 v101, 16, v101
	v_lshlrev_b32_e32 v100, 16, v100
	v_mfma_f32_16x16x32_bf16 v[134:137], v[208:211], v[52:55], v[134:137]
	v_mul_f32_e64 v210, v104, v100
	v_mul_f32_e64 v211, v105, v101
	v_mov_b32_e32 v100, v127
	v_mov_b32_e32 v101, v129
	v_pk_add_f32 v[100:101], v[166:167], v[100:101]
	v_and_b32_e32 v105, 0xffff0000, v97
	v_and_b32_e32 v104, 0xffff0000, v96
	v_mov_b32_e32 v127, v128
	v_pk_mul_f32 v[208:209], v[100:101], v[104:105]
	v_pk_add_f32 v[100:101], v[166:167], v[126:127]
	v_lshlrev_b32_e32 v97, 16, v97
	v_lshlrev_b32_e32 v96, 16, v96
	v_mfma_f32_16x16x32_bf16 v[114:117], v[204:207], v[76:79], v[114:117]
	v_mul_f32_e64 v206, v100, v96
	v_mul_f32_e64 v207, v101, v97
	v_mov_b32_e32 v96, v131
	v_mov_b32_e32 v97, v133
	v_pk_add_f32 v[96:97], v[168:169], v[96:97]
	v_and_b32_e32 v101, 0xffff0000, v93
	v_and_b32_e32 v100, 0xffff0000, v92
	v_mov_b32_e32 v131, v132
	v_pk_mul_f32 v[204:205], v[96:97], v[100:101]
	v_pk_add_f32 v[96:97], v[168:169], v[130:131]
	v_lshlrev_b32_e32 v93, 16, v93
	v_lshlrev_b32_e32 v92, 16, v92
	v_pk_mul_f32 v[202:203], v[96:97], v[92:93]
	v_mov_b32_e32 v92, v135
	v_mov_b32_e32 v93, v137
	v_pk_add_f32 v[92:93], v[170:171], v[92:93]
	v_and_b32_e32 v97, 0xffff0000, v89
	v_and_b32_e32 v96, 0xffff0000, v88
	v_mov_b32_e32 v135, v136
	v_pk_mul_f32 v[216:217], v[138:139], v[200:201]
	v_pk_mul_f32 v[200:201], v[92:93], v[96:97]
	v_pk_add_f32 v[92:93], v[170:171], v[134:135]
	v_lshlrev_b32_e32 v89, 16, v89
	v_lshlrev_b32_e32 v88, 16, v88
	v_pk_mul_f32 v[104:105], v[92:93], v[88:89]
	v_mov_b32_e32 v88, v223
	v_mov_b32_e32 v89, v225
	v_pk_add_f32 v[88:89], v[172:173], v[88:89]
	v_and_b32_e32 v93, 0xffff0000, v85
	v_and_b32_e32 v92, 0xffff0000, v84
	v_mov_b32_e32 v223, v224
	v_pk_mul_f32 v[100:101], v[88:89], v[92:93]
	v_pk_add_f32 v[88:89], v[172:173], v[222:223]
	v_lshlrev_b32_e32 v85, 16, v85
	v_lshlrev_b32_e32 v84, 16, v84
	v_pk_mul_f32 v[96:97], v[88:89], v[84:85]
	v_mov_b32_e32 v84, v227
	v_mov_b32_e32 v85, v229
	v_pk_add_f32 v[84:85], v[174:175], v[84:85]
	v_and_b32_e32 v89, 0xffff0000, v81
	v_and_b32_e32 v88, 0xffff0000, v80
	v_mov_b32_e32 v227, v228
	v_pk_mul_f32 v[92:93], v[84:85], v[88:89]
	v_pk_add_f32 v[84:85], v[174:175], v[226:227]
	v_lshlrev_b32_e32 v81, 16, v81
	v_lshlrev_b32_e32 v80, 16, v80
	v_pk_mul_f32 v[80:81], v[84:85], v[80:81]
	v_mov_b32_e32 v84, v115
	v_mov_b32_e32 v85, v117
	v_pk_add_f32 v[84:85], v[176:177], v[84:85]
	v_and_b32_e32 v89, 0xffff0000, v109
	v_and_b32_e32 v88, 0xffff0000, v108
	v_mov_b32_e32 v115, v116
	v_pk_mul_f32 v[88:89], v[84:85], v[88:89]
	v_pk_add_f32 v[84:85], v[176:177], v[114:115]
	ds_read_b64_tr_b16 v[114:115], v220 offset:352
	ds_read_b64_tr_b16 v[234:235], v220 offset:2592
	ds_read_b64_tr_b16 v[236:237], v220 offset:2912
	s_waitcnt lgkmcnt(2)
	v_mfma_f32_16x16x32_bf16 v[120:123], v[112:115], v[16:19], 0
	v_lshlrev_b32_e32 v109, 16, v109
	v_lshlrev_b32_e32 v108, 16, v108
	v_pk_mul_f32 v[84:85], v[84:85], v[108:109]
	v_mfma_f32_16x16x32_bf16 v[226:229], v[112:115], v[48:51], 0
	v_bfe_u32 v196, v216, 16, 1
	v_add3_u32 v196, v216, v196, s68
	v_bfe_u32 v195, v217, 16, 1
	v_mfma_f32_16x16x32_bf16 v[230:233], v[112:115], v[32:35], 0
	v_add3_u32 v195, v217, v195, s68
	v_mfma_f32_16x16x32_bf16 v[116:119], v[112:115], v[8:11], 0
	v_mfma_f32_16x16x32_bf16 v[124:127], v[112:115], v[24:27], 0
	v_mfma_f32_16x16x32_bf16 v[222:225], v[112:115], v[0:3], 0
	v_mfma_f32_16x16x32_bf16 v[132:135], v[112:115], v[4:7], 0
	v_mfma_f32_16x16x32_bf16 v[112:115], v[112:115], v[40:43], 0
	s_nop 5
	v_mov_b32_e32 v108, v223
	v_mov_b32_e32 v223, v224
	v_mov_b32_e32 v109, v225
	s_waitcnt lgkmcnt(0)
	v_mfma_f32_16x16x32_bf16 v[128:131], v[234:237], v[20:23], v[120:123]
	v_add_f32_e64 v222, v162, v222
	v_add_f32_e64 v223, v163, v223
	v_pk_add_f32 v[108:109], v[162:163], v[108:109]
	v_mfma_f32_16x16x32_bf16 v[120:123], v[234:237], v[56:59], v[226:229]
	v_mfma_f32_16x16x32_bf16 v[226:229], v[234:237], v[36:39], v[230:233]
	s_nop 2
	ds_read_b64_tr_b16 v[230:231], v220 offset:5152
	ds_read_b64_tr_b16 v[232:233], v220 offset:5472
	v_mfma_f32_16x16x32_bf16 v[136:139], v[234:237], v[12:15], v[116:119]
	v_mfma_f32_16x16x32_bf16 v[116:119], v[234:237], v[28:31], v[124:127]
	v_mfma_f32_16x16x32_bf16 v[112:115], v[234:237], v[44:47], v[112:115]
	s_waitcnt lgkmcnt(0)
	v_mfma_f32_16x16x32_bf16 v[124:127], v[230:233], v[52:55], v[116:119]
	v_mfma_f32_16x16x32_bf16 v[116:119], v[230:233], v[64:67], v[226:229]
	s_nop 2
	ds_read_b64_tr_b16 v[226:227], v220 offset:7712
	ds_read_b64_tr_b16 v[228:229], v220 offset:8032
	v_mfma_f32_16x16x32_bf16 v[112:115], v[230:233], v[72:75], v[112:115]
	s_waitcnt lgkmcnt(0)
; #define MFMA16(a, b, c) __builtin_amdgcn_mfma_f32_16x16x32_bf16((a), (b), (c), 0, 0, 0)
; __device__ __forceinline__ unsigned pk2(float lo, float hi) { return f2bf(lo) | (f2bf(hi) << 16); }
; __device__ __forceinline__ float bflo(unsigned w) { return __uint_as_float(w << 16); }
; __device__ __forceinline__ float bfhi(unsigned w) { return __uint_as_float(w & 0xffff0000u); }
; __device__ __forceinline__ void sgu_item(LAS unsigned char* wl, const bf16* proj, bf16* ymix, const float* vstat, const float* sgu_g, const bf16* Wm, const float* sgu_b, int chunk, int h, int lane) {
;     ...
;                 for (int tb = 2 * ks; tb < 8; ++tb) z[tb] = MFMA16(vf, wmf[f++], z[tb]);
;             }
; #pragma unroll
;             for (int tb = 0; tb < 8; ++tb) { const v4u uu = uu8[tb]; const unsigned ux = n == 0 ? uu.x : uu.z, uy = n == 0 ? uu.y : uu.w;
;                 v2u o; o.x = pk2(bflo(ux) * (z[tb][0] + bias[tb]), bfhi(ux) * (z[tb][1] + bias[tb])); o.y = pk2(bflo(uy) * (z[tb][2] + bias[tb]), bfhi(uy) * (z[tb][3] + bias[tb]));
;                 if (n == 0) olo[tb] = o;
;                 else { v4u w; w.x = olo[tb].x; w.y = olo[tb].y; w.z = o.x; w.w = o.y; *(v4u*)(ymix + (R0 + 16 * tb + r) * D + 512 + colv + 8 * q) = w; } }
	v_mfma_f32_16x16x32_bf16 v[116:119], v[226:229], v[68:71], v[116:119]
	v_mfma_f32_16x16x32_bf16 v[112:115], v[226:229], v[76:79], v[112:115]
	v_and_b32_e32 v227, 0xffff0000, v107
	v_and_b32_e32 v226, 0xffff0000, v106
	v_lshlrev_b32_e32 v107, 16, v107
	v_lshlrev_b32_e32 v106, 16, v106
	v_pk_mul_f32 v[106:107], v[222:223], v[106:107]
	v_pk_mul_f32 v[108:109], v[108:109], v[226:227]
	v_bfe_u32 v197, v106, 16, 1
	v_bfe_u32 v216, v107, 16, 1
	v_bfe_u32 v192, v109, 16, 1
	v_bfe_u32 v194, v108, 16, 1
	v_add3_u32 v107, v107, v216, s68
	v_add3_u32 v106, v106, v197, s68
	v_add3_u32 v108, v108, v194, s68
	v_add3_u32 v109, v109, v192, s68
	v_bfe_u32 v192, v214, 16, 1
	v_bfe_u32 v194, v215, 16, 1
	v_lshrrev_b32_e32 v106, 16, v106
	v_lshrrev_b32_e32 v107, 16, v107
	v_add3_u32 v194, v215, v194, s68
	v_add3_u32 v192, v214, v192, s68
	v_and_or_b32 v217, v109, s37, v107
	v_and_or_b32 v216, v108, s37, v106
	v_lshl_add_u64 v[106:107], v[182:183], 0, s[20:21]
	v_lshrrev_b32_e32 v192, 16, v192
	v_lshrrev_b32_e32 v194, 16, v194
	v_add_co_u32_e32 v108, vcc, s0, v106
	v_and_or_b32 v215, v195, s37, v194
	v_and_or_b32 v214, v196, s37, v192
	v_addc_co_u32_e32 v109, vcc, 0, v107, vcc
	global_store_dwordx4 v[108:109], v[214:217], off offset:1024
	v_mov_b32_e32 v108, v133
	v_mov_b32_e32 v109, v135
	v_mov_b32_e32 v133, v134
	v_pk_add_f32 v[108:109], v[164:165], v[108:109]
	v_and_b32_e32 v215, 0xffff0000, v103
	v_and_b32_e32 v214, 0xffff0000, v102
	v_pk_add_f32 v[132:133], v[164:165], v[132:133]
	v_lshlrev_b32_e32 v103, 16, v103
	v_lshlrev_b32_e32 v102, 16, v102
	v_pk_mul_f32 v[108:109], v[108:109], v[214:215]
	v_pk_mul_f32 v[102:103], v[132:133], v[102:103]
	v_bfe_u32 v134, v213, 16, 1
	v_bfe_u32 v132, v109, 16, 1
	v_bfe_u32 v133, v108, 16, 1
	v_bfe_u32 v135, v212, 16, 1
	v_add3_u32 v194, v213, v134, s68
	v_bfe_u32 v134, v102, 16, 1
	v_add3_u32 v192, v212, v135, s68
	v_add3_u32 v108, v108, v133, s68
	v_add3_u32 v109, v109, v132, s68
	v_bfe_u32 v132, v210, 16, 1
	v_bfe_u32 v133, v211, 16, 1
	v_bfe_u32 v135, v103, 16, 1
	v_add3_u32 v102, v102, v134, s68
	v_add3_u32 v103, v103, v135, s68
	v_add3_u32 v133, v211, v133, s68
	v_add3_u32 v132, v210, v132, s68
	v_lshrrev_b32_e32 v102, 16, v102
	s_mov_b32 s0, 0x10908000
	v_lshrrev_b32_e32 v132, 16, v132
	v_lshrrev_b32_e32 v133, 16, v133
	v_lshrrev_b32_e32 v103, 16, v103
	v_and_or_b32 v134, v108, s37, v102
	v_add_co_u32_e32 v102, vcc, s0, v106
	v_and_or_b32 v135, v109, s37, v103
	v_and_or_b32 v133, v194, s37, v133
	v_and_or_b32 v132, v192, s37, v132
	v_addc_co_u32_e32 v103, vcc, 0, v107, vcc
	global_store_dwordx4 v[102:103], v[132:135], off offset:1024
	v_mov_b32_e32 v102, v137
	v_mov_b32_e32 v103, v139
	v_pk_add_f32 v[102:103], v[166:167], v[102:103]
	v_and_b32_e32 v109, 0xffff0000, v99
	v_and_b32_e32 v108, 0xffff0000, v98
	v_mov_b32_e32 v137, v138
	v_pk_mul_f32 v[102:103], v[102:103], v[108:109]
	v_pk_add_f32 v[108:109], v[166:167], v[136:137]
	v_lshlrev_b32_e32 v99, 16, v99
	v_lshlrev_b32_e32 v98, 16, v98
	v_pk_mul_f32 v[98:99], v[108:109], v[98:99]
	v_bfe_u32 v133, v208, 16, 1
	v_bfe_u32 v108, v103, 16, 1
	v_bfe_u32 v109, v102, 16, 1
	v_add3_u32 v136, v208, v133, s68
	v_bfe_u32 v133, v98, 16, 1
	v_add3_u32 v102, v102, v109, s68
	v_add3_u32 v103, v103, v108, s68
	v_bfe_u32 v108, v206, 16, 1
	v_bfe_u32 v109, v207, 16, 1
	v_bfe_u32 v134, v99, 16, 1
	v_add3_u32 v98, v98, v133, s68
	v_bfe_u32 v132, v209, 16, 1
	v_add3_u32 v99, v99, v134, s68
	v_add3_u32 v109, v207, v109, s68
	v_add3_u32 v108, v206, v108, s68
	v_lshrrev_b32_e32 v98, 16, v98
	s_mov_b32 s0, 0x10910000
	v_add3_u32 v132, v209, v132, s68
	v_lshrrev_b32_e32 v108, 16, v108
	v_lshrrev_b32_e32 v109, 16, v109
	v_lshrrev_b32_e32 v99, 16, v99
	v_and_or_b32 v134, v102, s37, v98
	v_add_co_u32_e32 v98, vcc, s0, v106
	v_and_or_b32 v135, v103, s37, v99
	v_and_or_b32 v133, v132, s37, v109
	v_and_or_b32 v132, v136, s37, v108
	v_addc_co_u32_e32 v99, vcc, 0, v107, vcc
	global_store_dwordx4 v[98:99], v[132:135], off offset:1024
	v_mov_b32_e32 v98, v129
	v_mov_b32_e32 v99, v131
	v_pk_add_f32 v[98:99], v[168:169], v[98:99]
	v_and_b32_e32 v103, 0xffff0000, v95
	v_and_b32_e32 v102, 0xffff0000, v94
	v_mov_b32_e32 v129, v130
	v_pk_mul_f32 v[98:99], v[98:99], v[102:103]
	v_pk_add_f32 v[102:103], v[168:169], v[128:129]
	v_lshlrev_b32_e32 v95, 16, v95
	v_lshlrev_b32_e32 v94, 16, v94
	v_pk_mul_f32 v[94:95], v[102:103], v[94:95]
	v_bfe_u32 v102, v99, 16, 1
	v_bfe_u32 v103, v98, 16, 1
	v_add3_u32 v98, v98, v103, s68
	v_add3_u32 v99, v99, v102, s68
	v_bfe_u32 v102, v202, 16, 1
	v_bfe_u32 v103, v203, 16, 1
	v_bfe_u32 v128, v94, 16, 1
	v_bfe_u32 v129, v95, 16, 1
	v_bfe_u32 v108, v205, 16, 1
	v_bfe_u32 v109, v204, 16, 1
	v_add3_u32 v95, v95, v129, s68
	v_add3_u32 v94, v94, v128, s68
	v_add3_u32 v103, v203, v103, s68
	v_add3_u32 v102, v202, v102, s68
	v_add3_u32 v109, v204, v109, s68
	v_add3_u32 v108, v205, v108, s68
	v_lshrrev_b32_e32 v102, 16, v102
	v_lshrrev_b32_e32 v103, 16, v103
	v_lshrrev_b32_e32 v94, 16, v94
	v_lshrrev_b32_e32 v95, 16, v95
	v_and_or_b32 v131, v99, s37, v95
	v_and_or_b32 v130, v98, s37, v94
	v_and_or_b32 v129, v108, s37, v103
	v_and_or_b32 v128, v109, s37, v102
	v_lshl_add_u64 v[94:95], v[184:185], 0, s[20:21]
	global_store_dwordx4 v[94:95], v[128:131], off
	v_mov_b32_e32 v94, v125
	v_mov_b32_e32 v95, v127
	v_pk_add_f32 v[94:95], v[170:171], v[94:95]
; __device__ __forceinline__ unsigned pk2(float lo, float hi) { return f2bf(lo) | (f2bf(hi) << 16); }
; __device__ __forceinline__ float bflo(unsigned w) { return __uint_as_float(w << 16); }
; __device__ __forceinline__ float bfhi(unsigned w) { return __uint_as_float(w & 0xffff0000u); }
; #define LDS_WAIT() asm volatile("s_waitcnt lgkmcnt(0)" ::: "memory")
; __device__ __forceinline__ void sgu_item(LAS unsigned char* wl, const bf16* proj, bf16* ymix, const float* vstat, const float* sgu_g, const bf16* Wm, const float* sgu_b, int chunk, int h, int lane) {
;     ...
;             for (int tb = 0; tb < 8; ++tb) { const v4u uu = uu8[tb]; const unsigned ux = n == 0 ? uu.x : uu.z, uy = n == 0 ? uu.y : uu.w;
;                 v2u o; o.x = pk2(bflo(ux) * (z[tb][0] + bias[tb]), bfhi(ux) * (z[tb][1] + bias[tb])); o.y = pk2(bflo(uy) * (z[tb][2] + bias[tb]), bfhi(uy) * (z[tb][3] + bias[tb]));
;                 if (n == 0) olo[tb] = o;
;                 else { v4u w; w.x = olo[tb].x; w.y = olo[tb].y; w.z = o.x; w.w = o.y; *(v4u*)(ymix + (R0 + 16 * tb + r) * D + 512 + colv + 8 * q) = w; } }
;         }
;         LDS_WAIT();
	v_and_b32_e32 v99, 0xffff0000, v91
	v_and_b32_e32 v98, 0xffff0000, v90
	v_mov_b32_e32 v125, v126
	v_pk_mul_f32 v[94:95], v[94:95], v[98:99]
	v_pk_add_f32 v[98:99], v[170:171], v[124:125]
	v_lshlrev_b32_e32 v91, 16, v91
	v_lshlrev_b32_e32 v90, 16, v90
	v_pk_mul_f32 v[90:91], v[98:99], v[90:91]
	v_bfe_u32 v103, v200, 16, 1
	v_bfe_u32 v98, v95, 16, 1
	v_bfe_u32 v99, v94, 16, 1
	v_add3_u32 v108, v200, v103, s68
	v_bfe_u32 v103, v90, 16, 1
	v_mfma_f32_16x16x32_bf16 v[120:123], v[230:233], v[60:63], v[120:123]
	v_add3_u32 v94, v94, v99, s68
	v_add3_u32 v95, v95, v98, s68
	v_bfe_u32 v98, v104, 16, 1
	v_bfe_u32 v99, v105, 16, 1
	v_bfe_u32 v109, v91, 16, 1
	v_add3_u32 v90, v90, v103, s68
	v_bfe_u32 v102, v201, 16, 1
	v_add3_u32 v91, v91, v109, s68
	v_add3_u32 v99, v105, v99, s68
	v_add3_u32 v98, v104, v98, s68
	v_lshrrev_b32_e32 v90, 16, v90
	s_mov_b32 s0, 0x10920000
	v_add3_u32 v102, v201, v102, s68
	v_lshrrev_b32_e32 v98, 16, v98
	v_lshrrev_b32_e32 v99, 16, v99
	v_lshrrev_b32_e32 v91, 16, v91
	v_and_or_b32 v104, v94, s37, v90
	v_add_co_u32_e32 v90, vcc, s0, v106
	v_and_or_b32 v105, v95, s37, v91
	v_and_or_b32 v103, v102, s37, v99
	v_and_or_b32 v102, v108, s37, v98
	v_addc_co_u32_e32 v91, vcc, 0, v107, vcc
	global_store_dwordx4 v[90:91], v[102:105], off offset:1024
	v_mov_b32_e32 v90, v121
	v_mov_b32_e32 v91, v123
	v_pk_add_f32 v[90:91], v[172:173], v[90:91]
	v_and_b32_e32 v95, 0xffff0000, v87
	v_and_b32_e32 v94, 0xffff0000, v86
	v_mov_b32_e32 v121, v122
	v_pk_mul_f32 v[90:91], v[90:91], v[94:95]
	v_pk_add_f32 v[94:95], v[172:173], v[120:121]
	v_lshlrev_b32_e32 v87, 16, v87
	v_lshlrev_b32_e32 v86, 16, v86
	v_pk_mul_f32 v[86:87], v[94:95], v[86:87]
	v_bfe_u32 v99, v100, 16, 1
	v_bfe_u32 v94, v91, 16, 1
	v_bfe_u32 v95, v90, 16, 1
	v_bfe_u32 v98, v101, 16, 1
	v_add3_u32 v99, v100, v99, s68
	v_bfe_u32 v100, v86, 16, 1
	v_add3_u32 v98, v101, v98, s68
	v_add3_u32 v90, v90, v95, s68
	v_add3_u32 v91, v91, v94, s68
	v_bfe_u32 v94, v96, 16, 1
	v_bfe_u32 v95, v97, 16, 1
	v_bfe_u32 v101, v87, 16, 1
	v_add3_u32 v86, v86, v100, s68
	v_add3_u32 v87, v87, v101, s68
	v_add3_u32 v95, v97, v95, s68
	v_add3_u32 v94, v96, v94, s68
	v_lshrrev_b32_e32 v86, 16, v86
	s_mov_b32 s0, 0x10928000
	v_lshrrev_b32_e32 v94, 16, v94
	v_lshrrev_b32_e32 v95, 16, v95
	v_lshrrev_b32_e32 v87, 16, v87
	v_and_or_b32 v96, v90, s37, v86
	v_add_co_u32_e32 v86, vcc, s0, v106
	v_and_or_b32 v97, v91, s37, v87
	v_and_or_b32 v95, v98, s37, v95
	v_and_or_b32 v94, v99, s37, v94
	v_addc_co_u32_e32 v87, vcc, 0, v107, vcc
	global_store_dwordx4 v[86:87], v[94:97], off offset:1024
	v_mov_b32_e32 v86, v117
	v_mov_b32_e32 v87, v119
	v_pk_add_f32 v[86:87], v[174:175], v[86:87]
	v_and_b32_e32 v91, 0xffff0000, v83
	v_and_b32_e32 v90, 0xffff0000, v82
	v_mov_b32_e32 v117, v118
	v_pk_mul_f32 v[86:87], v[86:87], v[90:91]
	v_pk_add_f32 v[90:91], v[174:175], v[116:117]
	v_lshlrev_b32_e32 v83, 16, v83
	v_lshlrev_b32_e32 v82, 16, v82
	v_pk_mul_f32 v[82:83], v[90:91], v[82:83]
	v_bfe_u32 v94, v93, 16, 1
	v_bfe_u32 v90, v87, 16, 1
	v_bfe_u32 v91, v86, 16, 1
	v_bfe_u32 v95, v92, 16, 1
	v_add3_u32 v93, v93, v94, s68
	v_bfe_u32 v94, v82, 16, 1
	v_add3_u32 v92, v92, v95, s68
	v_add3_u32 v86, v86, v91, s68
	v_add3_u32 v87, v87, v90, s68
	v_bfe_u32 v90, v80, 16, 1
	v_bfe_u32 v91, v81, 16, 1
	v_bfe_u32 v95, v83, 16, 1
	v_add3_u32 v82, v82, v94, s68
	v_add3_u32 v83, v83, v95, s68
	v_add3_u32 v81, v81, v91, s68
	v_add3_u32 v80, v80, v90, s68
	v_lshrrev_b32_e32 v82, 16, v82
	s_mov_b32 s0, 0x10930000
	v_lshrrev_b32_e32 v80, 16, v80
	v_lshrrev_b32_e32 v81, 16, v81
	v_lshrrev_b32_e32 v83, 16, v83
	v_and_or_b32 v82, v86, s37, v82
	v_add_co_u32_e32 v86, vcc, s0, v106
	v_and_or_b32 v83, v87, s37, v83
	v_and_or_b32 v81, v93, s37, v81
	v_and_or_b32 v80, v92, s37, v80
	v_addc_co_u32_e32 v87, vcc, 0, v107, vcc
	global_store_dwordx4 v[86:87], v[80:83], off offset:1024
	v_lshlrev_b32_e32 v87, 16, v111
	v_lshlrev_b32_e32 v86, 16, v110
	v_mov_b32_e32 v80, v113
	v_mov_b32_e32 v81, v115
	v_pk_add_f32 v[80:81], v[176:177], v[80:81]
	v_and_b32_e32 v83, 0xffff0000, v111
	v_and_b32_e32 v82, 0xffff0000, v110
	v_mov_b32_e32 v113, v114
	v_pk_mul_f32 v[80:81], v[80:81], v[82:83]
	v_pk_add_f32 v[82:83], v[176:177], v[112:113]
	v_bfe_u32 v90, v89, 16, 1
	v_pk_mul_f32 v[82:83], v[82:83], v[86:87]
	v_bfe_u32 v86, v81, 16, 1
	v_bfe_u32 v87, v80, 16, 1
	v_bfe_u32 v91, v88, 16, 1
	v_add3_u32 v88, v88, v91, s68
	v_add3_u32 v89, v89, v90, s68
	v_add3_u32 v80, v80, v87, s68
	v_add3_u32 v81, v81, v86, s68
	v_bfe_u32 v86, v84, 16, 1
	v_bfe_u32 v87, v85, 16, 1
	v_bfe_u32 v90, v82, 16, 1
	v_bfe_u32 v91, v83, 16, 1
	v_add3_u32 v83, v83, v91, s68
	v_add3_u32 v82, v82, v90, s68
	v_add3_u32 v85, v85, v87, s68
	v_add3_u32 v84, v84, v86, s68
	v_lshrrev_b32_e32 v84, 16, v84
	v_lshrrev_b32_e32 v85, 16, v85
	v_lshrrev_b32_e32 v82, 16, v82
	v_lshrrev_b32_e32 v83, 16, v83
	v_and_or_b32 v83, v81, s37, v83
	v_and_or_b32 v82, v80, s37, v82
	v_and_or_b32 v81, v89, s37, v85
	v_and_or_b32 v80, v88, s37, v84
	v_lshl_add_u64 v[84:85], v[180:181], 0, s[20:21]
	global_store_dwordx4 v[84:85], v[80:83], off
	s_waitcnt lgkmcnt(0)
	s_add_u32 s20, s20, 64
	s_addc_u32 s21, s21, 0
	s_cmpk_lg_i32 s20, 0x100
	s_cbranch_scc1 .LBB0_511
	s_add_i32 s5, s5, s77
	s_add_i32 s4, s4, s7
	s_cmp_lt_i32 s5, s2
	s_cbranch_scc1 .LBB0_510
